# v54: v53 with the P2-done counter target taken from the grid-size register instead of the constant 256
# baseline (speedup 1.0000x reference)
; DI unsigned xb_ld(unsigned* p)              { return __hip_atomic_load(p, __ATOMIC_RELAXED, __HIP_MEMORY_SCOPE_AGENT); }
; DI void xcd_barrier_complete(unsigned* bar, unsigned x, unsigned& nloc, unsigned& nx) {
;     const unsigned G = gridDim.x * gridDim.y * gridDim.z;
;     unsigned sum, cnt, mine, sp = 0u;
;     for (;;) {
;         sum = 0u; cnt = 0u; mine = 0u;
; #pragma unroll
;         for (unsigned j = 0; j < 16; ++j) { const unsigned c = xb_ld(&bar[XB_XCNT(j)]); sum += c; cnt += (c > 0u) ? 1u : 0u; mine = (j == x) ? c : mine; }
;         if (sum == G) break;
.Lb3_prep:
	s_mov_b32 s12, s82
